# r15 + gdn_prep S2: in[23][h] table load issued with the first batch of loads
# baseline (speedup 1.0000x reference)
.LBB0_575:
	s_ashr_i32 s3, s2, 31
	s_barrier
	s_and_saveexec_b64 s[0:1], s[6:7]
	s_cbranch_execz .LBB0_582
	v_cmp_gt_i32_e32 vcc, s22, v146
	v_mov_b32_e32 v1, 0
	v_mov_b32_e32 v0, 0
	s_and_saveexec_b64 s[22:23], vcc
	s_cbranch_execz .LBB0_580
	v_add_u32_e32 v0, s25, v146
	v_ashrrev_i32_e32 v1, 31, v0
	v_readlane_b32 s26, v253, 42
	s_and_b32 s24, s24, 3
	v_lshlrev_b64 v[0:1], 5, v[0:1]
	v_readlane_b32 s27, v253, 43
	s_lshl_b32 s62, s24, 2
	v_readlane_b32 s24, v253, 38
	v_lshl_add_u64 v[0:1], s[26:27], 0, v[0:1]
	v_lshl_add_u64 v[0:1], v[0:1], 0, s[62:63]
	v_readlane_b32 s25, v253, 39
	global_load_dword v2, v[0:1], off offset:16
	s_nop 0
	global_load_dword v0, v[0:1], off
	s_load_dwordx2 s[24:25], s[24:25], 0xc0
	v_mov_b32_e32 v1, s62
	v_readlane_b32 s100, v253, 46
	v_readlane_b32 s101, v253, 47
	v_mov_b32_e32 v239, s62
	s_nop 4
	global_load_dword v239, v239, s[100:101]
	s_waitcnt lgkmcnt(0)
	global_load_dword v1, v1, s[24:25]
	s_mov_b32 s24, 0x41a00000
	s_waitcnt vmcnt(0)
	v_add_f32_e32 v1, v2, v1
	v_cmp_nlt_f32_e32 vcc, s24, v1
	s_and_saveexec_b64 s[24:25], vcc
	s_cbranch_execz .LBB0_579
	v_mul_f32_e32 v2, 0x3fb8aa3b, v1
	v_rndne_f32_e32 v3, v2
	s_mov_b32 s26, 0x3fb8aa3b
	v_sub_f32_e32 v4, v2, v3
	v_fma_f32 v2, v1, s26, -v2
	v_fmac_f32_e32 v2, 0x32a5705f, v1
	v_add_f32_e32 v2, v4, v2
	v_cvt_i32_f32_e32 v3, v3
	v_exp_f32_e32 v2, v2
	s_mov_b32 s26, 0xc2ce8ed0
	v_cmp_ngt_f32_e32 vcc, s26, v1
	s_mov_b32 s26, 0x42b17218
	v_ldexp_f32 v2, v2, v3
	v_cndmask_b32_e32 v2, 0, v2, vcc
	v_cmp_nlt_f32_e32 vcc, s26, v1
	s_mov_b32 s26, 0x3f2aaaab
	s_nop 0
	v_cndmask_b32_e32 v1, v221, v2, vcc
	v_add_f32_e32 v4, 1.0, v1
	v_add_f32_e32 v2, -1.0, v4
	v_sub_f32_e32 v3, v2, v4
	v_add_f32_e32 v3, 1.0, v3
	v_sub_f32_e32 v2, v1, v2
	v_add_f32_e32 v5, v2, v3
	v_frexp_mant_f32_e32 v6, v4
	v_cvt_f64_f32_e32 v[2:3], v4
	v_frexp_exp_i32_f64_e32 v2, v[2:3]
	v_cmp_gt_f32_e32 vcc, s26, v6
	s_mov_b32 s26, 0x3f317218
	s_nop 0
	v_subbrev_co_u32_e32 v10, vcc, 0, v2, vcc
	v_sub_u32_e32 v2, 0, v10
	v_ldexp_f32 v3, v4, v2
	v_add_f32_e32 v4, -1.0, v3
	v_add_f32_e32 v6, 1.0, v3
	v_ldexp_f32 v2, v5, v2
	v_add_f32_e32 v5, 1.0, v4
	v_add_f32_e32 v7, -1.0, v6
	v_sub_f32_e32 v5, v3, v5
	v_sub_f32_e32 v3, v3, v7
	v_add_f32_e32 v5, v2, v5
	v_add_f32_e32 v2, v2, v3
	v_add_f32_e32 v11, v6, v2
	v_rcp_f32_e32 v13, v11
	v_sub_f32_e32 v3, v6, v11
	v_add_f32_e32 v12, v2, v3
	v_add_f32_e32 v3, v4, v5
	v_mul_f32_e32 v15, v3, v13
	v_sub_f32_e32 v2, v4, v3
	v_mul_f32_e32 v4, v11, v15
	v_fma_f32 v6, v15, v11, -v4
	v_fmac_f32_e32 v6, v15, v12
	v_add_f32_e32 v14, v5, v2
	v_add_f32_e32 v2, v4, v6
	v_sub_f32_e32 v5, v3, v2
	v_pk_add_f32 v[8:9], v[2:3], v[4:5] neg_lo:[0,1] neg_hi:[0,1]
	v_mov_b32_e32 v7, v2
	v_pk_add_f32 v[2:3], v[8:9], v[6:7] neg_lo:[0,1] neg_hi:[0,1]
	s_nop 0
	v_add_f32_e32 v3, v14, v3
	v_add_f32_e32 v2, v2, v3
	v_add_f32_e32 v3, v5, v2
	v_mul_f32_e32 v14, v13, v3
	v_mul_f32_e32 v4, v11, v14
	v_fma_f32 v6, v14, v11, -v4
	v_fmac_f32_e32 v6, v14, v12
	v_sub_f32_e32 v5, v5, v3
	v_add_f32_e32 v11, v2, v5
	v_add_f32_e32 v2, v4, v6
	v_sub_f32_e32 v5, v3, v2
	v_pk_add_f32 v[8:9], v[2:3], v[4:5] neg_lo:[0,1] neg_hi:[0,1]
	v_mov_b32_e32 v7, v2
	v_pk_add_f32 v[2:3], v[8:9], v[6:7] neg_lo:[0,1] neg_hi:[0,1]
	s_nop 0
	v_add_f32_e32 v3, v11, v3
	v_add_f32_e32 v2, v2, v3
	v_add_f32_e32 v3, v15, v14
	v_add_f32_e32 v2, v5, v2
	v_sub_f32_e32 v4, v3, v15
	v_mul_f32_e32 v2, v13, v2
	v_sub_f32_e32 v4, v14, v4
	v_add_f32_e32 v4, v4, v2
	v_add_f32_e32 v6, v3, v4
	v_mul_f32_e32 v7, v6, v6
	v_fmamk_f32 v2, v7, 0x3e9b6dac, v204
	v_fmaak_f32 v35, v7, v2, 0x3f2aaada
	v_cvt_f32_i32_e32 v2, v10
	v_sub_f32_e32 v3, v6, v3
	v_sub_f32_e32 v3, v4, v3
	v_ldexp_f32 v8, v3, 1
	v_mul_f32_e32 v3, v6, v7
	v_ldexp_f32 v5, v6, 1
	v_pk_mul_f32 v[6:7], v[2:3], v[34:35]
	s_nop 0
	v_fma_f32 v4, v2, s26, -v6
	v_fmac_f32_e32 v4, 0xb102e308, v2
	v_pk_add_f32 v[2:3], v[6:7], v[4:5]
	s_mov_b32 s26, 0x7f800000
	v_sub_f32_e32 v5, v3, v5
	v_sub_f32_e32 v5, v7, v5
	v_add_f32_e32 v9, v8, v5
	v_mov_b32_e32 v8, v6
	v_pk_add_f32 v[6:7], v[2:3], v[6:7] neg_lo:[0,1] neg_hi:[0,1]
	v_pk_add_f32 v[10:11], v[2:3], v[8:9]
	v_mov_b32_e32 v5, v2
	v_mov_b32_e32 v7, v11
	v_pk_add_f32 v[12:13], v[4:5], v[6:7] neg_lo:[0,1] neg_hi:[0,1]
	v_pk_add_f32 v[4:5], v[4:5], v[6:7]
	v_mov_b32_e32 v8, v9
	v_pk_add_f32 v[6:7], v[4:5], v[2:3] op_sel:[1,0] op_sel_hi:[0,1] neg_lo:[0,1] neg_hi:[0,1]
	v_pk_add_f32 v[14:15], v[10:11], v[6:7] op_sel_hi:[1,0] neg_lo:[0,1] neg_hi:[0,1]
	v_mov_b32_e32 v10, v11
	v_mov_b32_e32 v11, v5
	v_pk_mov_b32 v[6:7], v[2:3], v[6:7] op_sel:[1,0]
	v_mov_b32_e32 v9, v2
	v_pk_add_f32 v[6:7], v[10:11], v[6:7] neg_lo:[0,1] neg_hi:[0,1]
	v_mov_b32_e32 v14, v12
	v_pk_add_f32 v[2:3], v[8:9], v[6:7] neg_lo:[0,1] neg_hi:[0,1]
	v_mov_b32_e32 v13, v5
	v_pk_add_f32 v[6:7], v[14:15], v[2:3]
	v_cmp_neq_f32_e32 vcc, s26, v1
	v_pk_add_f32 v[8:9], v[6:7], v[6:7] op_sel:[0,1] op_sel_hi:[1,0]
	s_mov_b32 s26, 0x33800000
	v_pk_add_f32 v[4:5], v[4:5], v[8:9] op_sel:[1,0] op_sel_hi:[0,1]
	v_mov_b32_e32 v7, v4
	v_pk_add_f32 v[10:11], v[6:7], v[12:13] neg_lo:[0,1] neg_hi:[0,1]
	v_mov_b32_e32 v3, v8
	v_sub_f32_e32 v5, v6, v10
	v_pk_add_f32 v[2:3], v[2:3], v[10:11] neg_lo:[0,1] neg_hi:[0,1]
	v_sub_f32_e32 v5, v12, v5
	v_add_f32_e32 v2, v2, v5
	v_add_f32_e32 v2, v2, v3
	v_add_f32_e32 v2, v4, v2
	v_cndmask_b32_e32 v2, v221, v2, vcc
	v_cmp_lt_f32_e64 vcc, |v1|, s26
	s_nop 1
	v_cndmask_b32_e32 v1, v2, v1, vcc
.LBB0_579:
	s_or_b64 exec, exec, s[24:25]
	v_readlane_b32 s24, v253, 44
	v_mov_b32_e32 v2, s62
	v_readlane_b32 s26, v253, 46
	v_readlane_b32 s27, v253, 47
	s_mov_b32 s24, 0x3fb8aa3b
	v_readlane_b32 s25, v253, 45
	s_nop 2
	v_mov_b32_e32 v2, v239
	s_waitcnt vmcnt(0)
	v_mul_f32_e32 v3, 0x3fb8aa3b, v2
	v_fma_f32 v4, v2, s24, -v3
	v_rndne_f32_e32 v5, v3
	v_fmac_f32_e32 v4, 0x32a5705f, v2
	v_sub_f32_e32 v3, v3, v5
	v_add_f32_e32 v3, v3, v4
	v_exp_f32_e32 v3, v3
	v_cvt_i32_f32_e32 v4, v5
	s_mov_b32 s24, 0xc2ce8ed0
	v_cmp_ngt_f32_e32 vcc, s24, v2
	s_mov_b32 s24, 0x42b17218
	v_ldexp_f32 v3, v3, v4
	v_cndmask_b32_e32 v3, 0, v3, vcc
	v_cmp_nlt_f32_e32 vcc, s24, v2
	s_mov_b32 s24, 0xbfb8aa3b
	s_nop 0
	v_cndmask_b32_e32 v2, v221, v3, vcc
	v_mul_f32_e64 v1, v1, -v2
	v_mul_f32_e32 v2, 0xbfb8aa3b, v0
	v_rndne_f32_e32 v3, v2
	v_sub_f32_e32 v4, v2, v3
	v_fma_f32 v2, v0, s24, -v2
	v_fmac_f32_e32 v2, 0xb2a5705f, v0
	v_add_f32_e32 v2, v4, v2
	v_exp_f32_e32 v2, v2
	v_cvt_i32_f32_e32 v3, v3
	s_mov_b32 s24, 0x42ce8ed0
	v_cmp_nlt_f32_e32 vcc, s24, v0
	s_mov_b32 s24, 0xc2b17218
	v_ldexp_f32 v2, v2, v3
	v_cndmask_b32_e32 v2, 0, v2, vcc
	v_cmp_ngt_f32_e32 vcc, s24, v0
	s_nop 1
	v_cndmask_b32_e32 v0, v221, v2, vcc
	v_add_f32_e32 v0, 1.0, v0
	v_div_scale_f32 v2, s[24:25], v0, v0, 1.0
	v_rcp_f32_e32 v3, v2
	s_nop 0
	v_fma_f32 v4, -v2, v3, 1.0
	v_fmac_f32_e32 v3, v4, v3
	v_div_scale_f32 v4, vcc, 1.0, v0, 1.0
	v_mul_f32_e32 v5, v4, v3
	v_fma_f32 v6, -v2, v5, v4
	v_fmac_f32_e32 v5, v6, v3
	v_fma_f32 v2, -v2, v5, v4
	v_div_fmas_f32 v2, v2, v3, v5
	v_div_fixup_f32 v0, v2, v0, 1.0
